# v63 + hm3 C=0 first-touch after each fold with the selector branch ahead of the barrier + dattn +0 seed add removed
# speedup vs baseline: 1.0008x; 1.0008x over previous
.LBB0_1002:
	s_cmp_eq_u32 s22, 0
	s_cbranch_scc1 .Lhm3_zc
	s_waitcnt lgkmcnt(0)
	s_barrier
	v_mfma_f32_16x16x32_bf16 v[126:129], v[146:149], v[186:189], v[126:129]
	v_mfma_f32_16x16x32_bf16 v[122:125], v[154:157], v[186:189], v[122:125]
	v_mfma_f32_16x16x32_bf16 v[110:113], v[146:149], v[178:181], v[110:113]
	v_mfma_f32_16x16x32_bf16 v[106:109], v[154:157], v[178:181], v[106:109]
	v_mfma_f32_16x16x32_bf16 v[94:97], v[146:149], v[170:173], v[94:97]
	v_mfma_f32_16x16x32_bf16 v[90:93], v[154:157], v[170:173], v[90:93]
	v_mfma_f32_16x16x32_bf16 v[78:81], v[146:149], v[162:165], v[78:81]
	v_mfma_f32_16x16x32_bf16 v[74:77], v[154:157], v[162:165], v[74:77]
	v_mfma_f32_16x16x32_bf16 v[126:129], v[150:153], v[190:193], v[126:129]
	v_mfma_f32_16x16x32_bf16 v[122:125], v[158:161], v[190:193], v[122:125]
	v_mfma_f32_16x16x32_bf16 v[110:113], v[150:153], v[182:185], v[110:113]
	v_mfma_f32_16x16x32_bf16 v[106:109], v[158:161], v[182:185], v[106:109]
	v_mfma_f32_16x16x32_bf16 v[94:97], v[150:153], v[174:177], v[94:97]
	v_mfma_f32_16x16x32_bf16 v[90:93], v[158:161], v[174:177], v[90:93]
	v_mfma_f32_16x16x32_bf16 v[78:81], v[150:153], v[166:169], v[78:81]
	v_mfma_f32_16x16x32_bf16 v[74:77], v[158:161], v[166:169], v[74:77]
	v_mfma_f32_16x16x32_bf16 v[118:121], v[130:133], v[186:189], v[118:121]
	v_mfma_f32_16x16x32_bf16 v[114:117], v[138:141], v[186:189], v[114:117]
	v_mfma_f32_16x16x32_bf16 v[102:105], v[130:133], v[178:181], v[102:105]
	v_mfma_f32_16x16x32_bf16 v[98:101], v[138:141], v[178:181], v[98:101]
	v_mfma_f32_16x16x32_bf16 v[86:89], v[130:133], v[170:173], v[86:89]
	v_mfma_f32_16x16x32_bf16 v[82:85], v[138:141], v[170:173], v[82:85]
	v_mfma_f32_16x16x32_bf16 v[70:73], v[130:133], v[162:165], v[70:73]
	v_mfma_f32_16x16x32_bf16 v[66:69], v[138:141], v[162:165], v[66:69]
	v_mfma_f32_16x16x32_bf16 v[118:121], v[134:137], v[190:193], v[118:121]
	v_mfma_f32_16x16x32_bf16 v[114:117], v[142:145], v[190:193], v[114:117]
	v_mfma_f32_16x16x32_bf16 v[102:105], v[134:137], v[182:185], v[102:105]
	v_mfma_f32_16x16x32_bf16 v[98:101], v[142:145], v[182:185], v[98:101]
	v_mfma_f32_16x16x32_bf16 v[86:89], v[134:137], v[174:177], v[86:89]
	v_mfma_f32_16x16x32_bf16 v[82:85], v[142:145], v[174:177], v[82:85]
	v_mfma_f32_16x16x32_bf16 v[70:73], v[134:137], v[166:169], v[70:73]
	v_mfma_f32_16x16x32_bf16 v[66:69], v[142:145], v[166:169], v[66:69]

.Lhm3_zc:
	s_waitcnt lgkmcnt(0)
	s_barrier
	v_mfma_f32_16x16x32_bf16 v[126:129], v[146:149], v[186:189], 0
	v_mfma_f32_16x16x32_bf16 v[122:125], v[154:157], v[186:189], 0
	v_mfma_f32_16x16x32_bf16 v[110:113], v[146:149], v[178:181], 0
	v_mfma_f32_16x16x32_bf16 v[106:109], v[154:157], v[178:181], 0
	v_mfma_f32_16x16x32_bf16 v[94:97], v[146:149], v[170:173], 0
	v_mfma_f32_16x16x32_bf16 v[90:93], v[154:157], v[170:173], 0
	v_mfma_f32_16x16x32_bf16 v[78:81], v[146:149], v[162:165], 0
	v_mfma_f32_16x16x32_bf16 v[74:77], v[154:157], v[162:165], 0
	v_mfma_f32_16x16x32_bf16 v[126:129], v[150:153], v[190:193], v[126:129]
	v_mfma_f32_16x16x32_bf16 v[122:125], v[158:161], v[190:193], v[122:125]
	v_mfma_f32_16x16x32_bf16 v[110:113], v[150:153], v[182:185], v[110:113]
	v_mfma_f32_16x16x32_bf16 v[106:109], v[158:161], v[182:185], v[106:109]
	v_mfma_f32_16x16x32_bf16 v[94:97], v[150:153], v[174:177], v[94:97]
	v_mfma_f32_16x16x32_bf16 v[90:93], v[158:161], v[174:177], v[90:93]
	v_mfma_f32_16x16x32_bf16 v[78:81], v[150:153], v[166:169], v[78:81]
	v_mfma_f32_16x16x32_bf16 v[74:77], v[158:161], v[166:169], v[74:77]
	v_mfma_f32_16x16x32_bf16 v[118:121], v[130:133], v[186:189], 0
	v_mfma_f32_16x16x32_bf16 v[114:117], v[138:141], v[186:189], 0
	v_mfma_f32_16x16x32_bf16 v[102:105], v[130:133], v[178:181], 0
	v_mfma_f32_16x16x32_bf16 v[98:101], v[138:141], v[178:181], 0
	v_mfma_f32_16x16x32_bf16 v[86:89], v[130:133], v[170:173], 0
	v_mfma_f32_16x16x32_bf16 v[82:85], v[138:141], v[170:173], 0
	v_mfma_f32_16x16x32_bf16 v[70:73], v[130:133], v[162:165], 0
	v_mfma_f32_16x16x32_bf16 v[66:69], v[138:141], v[162:165], 0
	v_mfma_f32_16x16x32_bf16 v[118:121], v[134:137], v[190:193], v[118:121]
	v_mfma_f32_16x16x32_bf16 v[114:117], v[142:145], v[190:193], v[114:117]
	v_mfma_f32_16x16x32_bf16 v[102:105], v[134:137], v[182:185], v[102:105]
	v_mfma_f32_16x16x32_bf16 v[98:101], v[142:145], v[182:185], v[98:101]
	v_mfma_f32_16x16x32_bf16 v[86:89], v[134:137], v[174:177], v[86:89]
	v_mfma_f32_16x16x32_bf16 v[82:85], v[142:145], v[174:177], v[82:85]
	v_mfma_f32_16x16x32_bf16 v[70:73], v[134:137], v[166:169], v[70:73]
	v_mfma_f32_16x16x32_bf16 v[66:69], v[142:145], v[166:169], v[66:69]
	s_branch .Lhm3_join
